# MLA static units: the second query block's first K/V tile and query fragments are requested in the first block's last loop iteration (next-unit prefetch across the epilogue)
# speedup vs baseline: 1.0095x; 1.0064x over previous
;     ...
;     const int q0 = NMETA + 256 * qi;
;     const int qw0 = q0 + 32 * wid;
;     const int myq = qw0 + ln;
;     const int nkt = (q0 + 255) / 64 + 1;
;     bf16x8 qf[KS];
; #pragma unroll
;     for (int ks = 0; ks < KS; ++ks) {
;         if (ks < 4) qf[ks] = *(const bf16x8*)(qa + (size_t)myq * ldqa + ks * 16 + h * 8);
;         else qf[ks] = *(const bf16x8*)(qb + (size_t)myq * ldqb + (ks - 4) * 16 + h * 8);
;     }
;     ...
;     auto gload = [&](int j) {
; #pragma unroll
;         for (int r = 0; r < NK2; ++r) {
;             const int c = tid + NT * r;
;             if (c < 64 * KCH) { const int row = c / KCH, ch = c - row * KCH; kr[r] = *(const u32x4*)(kbase + (size_t)(64 * j + row) * ldk + ch * 8); }
;         }
;         { const int row = tid >> 3, ch = tid & 7; vr = *(const u32x4*)(vt + (size_t)row * LP + 64 * j + ch * 8); }
;         if (FOX) { if (tid < 64) br = bias[64 * j + tid]; }
.LBB0_737:
	s_and_b64 s[10:11], s[8:9], exec
	s_cselect_b32 s12, s59, s58
	s_cbranch_scc0 .Lmp_pro
	v_add3_u32 v159, v137, s12, 16
	v_add_u32_e32 v2, v159, v208
	v_ashrrev_i32_e32 v3, 31, v2
	v_lshlrev_b64 v[4:5], 10, v[2:3]
	v_lshlrev_b64 v[2:3], 11, v[2:3]
	v_lshl_add_u64 v[2:3], v[160:161], 0, v[2:3]
	global_load_dwordx4 v[66:69], v[2:3], off
	global_load_dwordx4 v[70:73], v[2:3], off offset:32
	global_load_dwordx4 v[74:77], v[2:3], off offset:64
	global_load_dwordx4 v[78:81], v[2:3], off offset:96
	v_lshl_add_u64 v[2:3], v[170:171], 0, v[4:5]
	global_load_dwordx4 v[82:85], v[2:3], off
	global_load_dwordx4 v[86:89], v[2:3], off offset:32
	s_add_i32 s13, s12, 0x10f
	s_and_b32 s2, s13, 0x1f00
	s_and_saveexec_b64 s[10:11], s[4:5]
	s_cbranch_execz .LBB0_739
	v_add_u32_e32 v1, s2, v184
	v_mad_i64_i32 v[2:3], s[14:15], v1, s70, v[164:165]
	global_load_dwordx4 v[90:93], v[2:3], off

;     ...
;     f32x16 o[2];
; #pragma unroll
;     for (int d = 0; d < 2; ++d)
; #pragma unroll
;         for (int r = 0; r < 16; ++r) o[d][r] = 0.f;
;     float m = -INFINITY, lsum = 0.f;
;     ...
;     auto gload = [&](int j) {
; #pragma unroll
;         for (int r = 0; r < NK2; ++r) {
;             const int c = tid + NT * r;
;             if (c < 64 * KCH) { const int row = c / KCH, ch = c - row * KCH; kr[r] = *(const u32x4*)(kbase + (size_t)(64 * j + row) * ldk + ch * 8); }
;         }
;         { const int row = tid >> 3, ch = tid & 7; vr = *(const u32x4*)(vt + (size_t)row * LP + 64 * j + ch * 8); }
;         if (FOX) { if (tid < 64) br = bias[64 * j + tid]; }
;     };
;     auto lstore = [&](int st) {
;         unsigned char* base = lds + st * STG;
; #pragma unroll
;         for (int r = 0; r < NK2; ++r) {
;             const int c = tid + NT * r;
;             if (c < 64 * KCH) { const int row = c / KCH, ch = c - row * KCH; *(u32x4*)(base + row * KROW + ch * 16) = kr[r]; }
;         }
;         { const int row = tid >> 3, ch = tid & 7; unsigned char* d = base + KBYTES + row * VROW + ch * 16;
;           *(u32x2*)d = (u32x2){vr[0], vr[1]}; *(u32x2*)(d + 8) = (u32x2){vr[2], vr[3]}; }
;         if (FOX) { if (tid < 64) *(float*)(base + KBYTES + VBYTES + tid * 4) = br; }
;     };
;     const int jlast = nkt - 1;
;     gload(jlast); lstore(0);
;     __syncthreads();
.Lmp_pro:
	v_add3_u32 v159, v137, s12, 16
	s_add_i32 s13, s12, 0x10f
	s_and_b32 s2, s13, 0x1f00
	s_and_saveexec_b64 s[10:11], s[4:5]
	s_cbranch_execz .Lmp_743
	s_waitcnt vmcnt(11)
	ds_write_b128 v211, v[90:93] offset:2048
.Lmp_743:
	s_or_b64 exec, exec, s[10:11]
	s_and_saveexec_b64 s[10:11], s[6:7]
	s_cbranch_execz .Lmp_745
	s_waitcnt vmcnt(11)
	ds_write_b128 v212, v[94:97] offset:2048
.Lmp_745:
	s_or_b64 exec, exec, s[10:11]
	s_and_b32 s10, s13, 0x1fc0
	v_add_u32_e32 v1, s12, v151
	v_subrev_u32_e32 v219, s10, v1
	v_add_u32_e32 v1, s10, v184
	s_xor_b64 s[48:49], s[8:9], -1
	v_mad_i64_i32 v[176:177], s[8:9], v1, s70, v[172:173]
	v_add_u32_e32 v1, s10, v189
	v_mov_b32_e32 v14, v0
	v_mov_b32_e32 v15, v0
	v_mad_i64_i32 v[178:179], s[8:9], v1, s70, v[174:175]
	v_mov_b32_e32 v1, v0
	v_mov_b32_e32 v2, v0
	v_mov_b32_e32 v3, v0
	v_mov_b32_e32 v4, v0
	v_mov_b32_e32 v5, v0
	v_mov_b32_e32 v6, v0
	v_mov_b32_e32 v7, v0
	v_mov_b32_e32 v8, v0
	v_mov_b32_e32 v9, v0
	v_mov_b32_e32 v10, v0
	v_mov_b32_e32 v11, v0
	v_mov_b32_e32 v12, v0
	v_mov_b32_e32 v13, v0
	v_mov_b64_e32 v[32:33], v[14:15]
	v_mov_b64_e32 v[30:31], v[12:13]
	v_mov_b64_e32 v[28:29], v[10:11]
	v_mov_b64_e32 v[26:27], v[8:9]
	v_mov_b64_e32 v[24:25], v[6:7]
	v_mov_b64_e32 v[22:23], v[4:5]
	v_mov_b64_e32 v[20:21], v[2:3]
	v_mov_b64_e32 v[18:19], v[0:1]
	v_mov_b64_e32 v[16:17], v[14:15]
	s_lshr_b32 s2, s13, 6
	v_add_u32_e32 v218, 31, v159
	s_sub_i32 s42, s10, 64
	s_mov_b32 s60, 0
	v_mov_b32_e32 v220, 0
	v_mov_b32_e32 v248, 0
	v_mov_b32_e32 v249, 0
	v_mov_b32_e32 v250, 0
	v_mov_b32_e32 v251, 0
	v_mov_b32_e32 v252, 0
	v_mov_b32_e32 v253, 0
	v_mov_b32_e32 v254, 0
	v_mov_b32_e32 v255, 0
	v_mov_b32_e32 v221, 0xf149f2ca
	v_mov_b32_e32 v230, 0
	v_mov_b32_e32 v231, 0
	v_mov_b32_e32 v232, 0
	v_mov_b32_e32 v233, 0
	v_mov_b32_e32 v234, 0
	v_mov_b32_e32 v235, 0
	v_mov_b32_e32 v236, 0
	v_mov_b32_e32 v237, 0
	v_mov_b32_e32 v238, 0
	v_mov_b32_e32 v239, 0
	v_mov_b32_e32 v240, 0
	v_mov_b32_e32 v241, 0
	v_mov_b32_e32 v242, 0
	v_mov_b32_e32 v243, 0
	v_mov_b32_e32 v244, 0
	v_mov_b32_e32 v245, 0
	v_mov_b32_e32 v246, 0
	v_mov_b64_e32 v[14:15], v[12:13]
	v_mov_b64_e32 v[12:13], v[10:11]
	v_mov_b64_e32 v[10:11], v[8:9]
	v_mov_b64_e32 v[8:9], v[6:7]
	v_mov_b64_e32 v[6:7], v[4:5]
	v_mov_b64_e32 v[4:5], v[2:3]
	v_mov_b64_e32 v[2:3], v[0:1]
	s_waitcnt vmcnt(4)
	ds_write2_b64 v213, v[98:99], v[100:101] offset1:1
	s_waitcnt lgkmcnt(0)
	s_barrier
	s_branch .LBB0_748
.Lmp_lastG:
	s_and_b64 vcc, exec, s[48:49]
	s_cbranch_vccnz .LBB0_754
	s_add_i32 s100, s58, 0x10f
	s_and_b32 s100, s100, 0x1f00
	s_and_saveexec_b64 s[98:99], s[4:5]
	s_cbranch_execz .Lmp_k1
	v_add_u32_e32 v1, s100, v184
	v_mad_i64_i32 v[34:35], s[14:15], v1, s70, v[164:165]
	global_load_dwordx4 v[90:93], v[34:35], off
.Lmp_k1:
	s_or_b64 exec, exec, s[98:99]
	s_and_saveexec_b64 s[98:99], s[6:7]
	s_cbranch_execz .Lmp_k2
	v_add_u32_e32 v1, s100, v189
	v_mad_i64_i32 v[34:35], s[14:15], v1, s70, v[166:167]
	global_load_dwordx4 v[94:97], v[34:35], off
.Lmp_k2:
	s_or_b64 exec, exec, s[98:99]
	s_lshl_b32 s100, s100, 1
	s_mov_b32 s101, 0
	v_lshl_add_u64 v[34:35], v[162:163], 0, s[100:101]
	global_load_dwordx4 v[98:101], v[34:35], off
	s_branch .LBB0_754
.Lmp_last:
	s_and_b64 vcc, exec, s[48:49]
	s_cbranch_vccnz .LBB0_747
	v_add3_u32 v40, v137, s58, 16
	v_add_u32_e32 v40, v40, v208
	v_ashrrev_i32_e32 v41, 31, v40
	v_lshlrev_b64 v[42:43], 10, v[40:41]
	v_lshlrev_b64 v[40:41], 11, v[40:41]
	v_lshl_add_u64 v[40:41], v[160:161], 0, v[40:41]
	global_load_dwordx4 v[66:69], v[40:41], off
	global_load_dwordx4 v[70:73], v[40:41], off offset:32
	global_load_dwordx4 v[74:77], v[40:41], off offset:64
	global_load_dwordx4 v[78:81], v[40:41], off offset:96
	v_lshl_add_u64 v[42:43], v[170:171], 0, v[42:43]
	global_load_dwordx4 v[82:85], v[42:43], off
	global_load_dwordx4 v[86:89], v[42:43], off offset:32
	s_branch .LBB0_747
